# memory-key normalisation moved from phase 2 (all workgroups) to the 192 workgroups idle in phase 3's last partial round
# baseline (speedup 1.0000x reference)
.LBB0_228:
	v_readlane_b32 s0, v243, 19
	s_cmp_lt_i32 s0, 2
	s_mov_b64 s[22:23], -1
	s_cbranch_scc1 .LBB0_237
	v_readlane_b32 s0, v243, 19
	s_cmp_eq_u32 s0, 3
	s_cbranch_scc0 .LBB0_236
	v_mov_b32_e32 v4, v220
	v_readlane_b32 s0, v248, 58
	s_sub_i32 s0, s0, 0x200
	s_cmp_lt_i32 s0, 0
	s_cselect_b32 s0, 0x2000, s0
	v_ashrrev_i32_e32 v1, 6, v4
	s_nop 0
	v_add_u32_e32 v1, s0, v1
	s_movk_i32 s0, 0x2000
	v_cmp_gt_i32_e32 vcc, s0, v1
	s_and_saveexec_b64 s[22:23], vcc
	s_cbranch_execz .LBB0_235
	v_mbcnt_hi_u32_b32 v2, -1, v227
	s_waitcnt lgkmcnt(0)
	v_and_b32_e32 v5, 64, v2
	v_xor_b32_e32 v3, 1, v2
	v_add_u32_e32 v7, 64, v5
	v_cmp_lt_i32_e32 vcc, v3, v7
	v_and_b32_e32 v6, 63, v4
	v_readlane_b32 s48, v250, 34
	v_cndmask_b32_e32 v3, v2, v3, vcc
	v_lshlrev_b32_e32 v5, 2, v3
	v_xor_b32_e32 v3, 2, v2
	v_cmp_lt_i32_e32 vcc, v3, v7
	v_and_b32_e32 v19, 32, v4
	v_bfe_u32 v20, v4, 1, 4
	v_cndmask_b32_e32 v3, v2, v3, vcc
	v_lshlrev_b32_e32 v14, 2, v3
	v_xor_b32_e32 v3, 4, v2
	v_cmp_lt_i32_e32 vcc, v3, v7
	v_lshlrev_b32_e32 v8, 2, v6
	v_readlane_b32 s56, v250, 42
	v_cndmask_b32_e32 v3, v2, v3, vcc
	v_lshlrev_b32_e32 v15, 2, v3
	v_xor_b32_e32 v3, 8, v2
	v_cmp_lt_i32_e32 vcc, v3, v7
	v_readlane_b32 s57, v250, 43
	s_mov_b64 s[28:29], 0
	v_cndmask_b32_e32 v3, v2, v3, vcc
	v_lshlrev_b32_e32 v16, 2, v3
	v_xor_b32_e32 v3, 16, v2
	v_cmp_lt_i32_e32 vcc, v3, v7
	v_lshlrev_b32_e32 v8, 1, v8
	v_readlane_b32 s49, v250, 35
	v_cndmask_b32_e32 v3, v2, v3, vcc
	v_lshlrev_b32_e32 v17, 2, v3
	v_xor_b32_e32 v3, 32, v2
	v_cmp_lt_i32_e32 vcc, v3, v7
	v_lshlrev_b32_e32 v7, 2, v4
	v_bfe_u32 v4, v4, 6, 2
	v_cndmask_b32_e32 v2, v2, v3, vcc
	v_lshlrev_b32_e32 v18, 2, v2
	v_lshlrev_b32_e32 v2, 4, v6
	v_mov_b32_e32 v3, v0
	v_and_b32_e32 v10, 4, v7
	v_cmp_eq_u32_e32 vcc, 0, v6
	v_lshlrev_b32_e32 v6, 8, v4
	v_lshl_add_u64 v[2:3], s[56:57], 0, v[2:3]
	v_lshlrev_b32_e32 v6, 1, v6
	v_lshlrev_b32_e32 v10, 1, v10
	v_readlane_b32 s50, v250, 36
	v_readlane_b32 s51, v250, 37
	v_readlane_b32 s52, v250, 38
	v_readlane_b32 s53, v250, 39
	v_readlane_b32 s54, v250, 40
	v_readlane_b32 s55, v250, 41
	v_readlane_b32 s58, v250, 44
	v_readlane_b32 s59, v250, 45
	v_readlane_b32 s60, v250, 46
	v_readlane_b32 s61, v250, 47
	v_readlane_b32 s62, v250, 48
	v_readlane_b32 s63, v250, 49
	s_branch .LBB0_233
.LBB0_232:
	s_or_b64 exec, exec, s[34:35]
	v_add_u32_e32 v1, 0x600, v1
	s_movk_i32 s0, 0x1fff
	v_cmp_lt_i32_e64 s[38:39], s0, v1
	s_or_b64 s[28:29], s[38:39], s[28:29]
	s_andn2_b64 exec, exec, s[28:29]
	s_cbranch_execz .LBB0_235
